# prompt attention steady loop hand-interleaved (MFMA/VALU/LDS reads), same numerics
# speedup vs baseline: 1.0203x; 1.0203x over previous
.LBB0_822:
	s_add_i32 s2, s52, 0xfffff000
	buffer_load_dwordx2 v[108:109], v161, s[12:15], s2 offen
	s_add_i32 s3, s53, 0xfe020000
	buffer_load_dwordx4 v[104:107], v150, s[12:15], s3 offen
	s_add_i32 s4, s53, 0xfffe0000
	buffer_load_dwordx4 v[100:103], v150, s[12:15], s4 offen
	ds_read_b64_tr_b16 v[200:201], v162 offset:26624
	ds_read_b64_tr_b16 v[202:203], v162 offset:28160
	ds_read_b64_tr_b16 v[204:205], v162 offset:26688
	ds_read_b64_tr_b16 v[206:207], v162 offset:28224
	ds_read_b64_tr_b16 v[208:209], v162 offset:29696
	ds_read_b64_tr_b16 v[210:211], v162 offset:31232
	ds_read_b64_tr_b16 v[212:213], v162 offset:29760
	ds_read_b64_tr_b16 v[214:215], v162 offset:31296
	v_max3_f32 v2, v84, v36, v85
	v_max3_f32 v110, v37, v86, v38
	v_max3_f32 v2, v2, v87, v39
	v_max3_f32 v110, v110, v88, v40
	s_waitcnt lgkmcnt(6)
	v_mfma_f32_32x32x16_bf16 v[4:19], v[200:203], v[144:147], v[4:19]
	ds_read_b64_tr_b16 v[216:217], v162 offset:32768
	v_max3_f32 v2, v2, v89, v41
	v_max3_f32 v110, v110, v90, v42
	v_max3_f32 v2, v2, v91, v43
	v_max3_f32 v110, v110, v92, v44
	v_max3_f32 v2, v2, v93, v45
	v_max3_f32 v110, v110, v94, v46
	v_max3_f32 v2, v2, v95, v47
	s_waitcnt lgkmcnt(5)
	v_mfma_f32_32x32x16_bf16 v[20:35], v[204:207], v[144:147], v[20:35]
	ds_read_b64_tr_b16 v[218:219], v162 offset:34304
	ds_read_b64_tr_b16 v[234:235], v162 offset:32832
	v_max3_f32 v110, v110, v96, v48
	v_max3_f32 v2, v2, v97, v49
	v_max3_f32 v110, v110, v98, v50
	v_max3_f32 v2, v2, v110, v99
	v_max_f32_e32 v2, v2, v51
	v_mov_b32_e32 v111, v2
	v_add_f32_e32 v115, 0x41000000, v159
	s_waitcnt lgkmcnt(5)
	v_mfma_f32_32x32x16_bf16 v[4:19], v[208:211], v[140:143], v[4:19]
	ds_read_b64_tr_b16 v[236:237], v162 offset:34368
	ds_read_b64_tr_b16 v[238:239], v162 offset:35840
	v_add_u32_e32 v163, 0, v162
	v_permlane32_swap_b32_e32 v2, v111
	v_max_f32_e32 v2, v2, v111
	v_mul_f32_e32 v2, 0x3e16c740, v2
	v_cmp_gt_f32_e32 vcc, v2, v115
	v_max_f32_e32 v114, v159, v2
	v_sub_f32_e32 v112, v159, v114
	s_waitcnt lgkmcnt(5)
	v_mfma_f32_32x32x16_bf16 v[20:35], v[212:215], v[140:143], v[20:35]
	ds_read_b64_tr_b16 v[240:241], v162 offset:37376
	ds_read_b64_tr_b16 v[242:243], v162 offset:35904
	v_exp_f32_e32 v112, v112
	s_cmp_eq_u64 vcc, 0
	s_cselect_b64 s[2:3], -1, 0
	v_cndmask_b32_e64 v159, v114, v159, s[2:3]
	v_mul_f32_e32 v116, v152, v112
	v_cndmask_b32_e64 v152, v116, v152, s[2:3]
	v_fma_f32 v84, v84, s72, -v159
	v_fma_f32 v36, v36, s72, -v159
	v_fma_f32 v85, v85, s72, -v159
	s_waitcnt lgkmcnt(5)
	v_mfma_f32_32x32x16_bf16 v[4:19], v[216:219], v[136:139], v[4:19]
	ds_read_b64_tr_b16 v[244:245], v162 offset:37440
	ds_read_b128 v[246:249], v156 offset:51200
	v_exp_f32_e32 v84, v84
	v_fma_f32 v37, v37, s72, -v159
	v_exp_f32_e32 v36, v36
	v_fma_f32 v86, v86, s72, -v159
	v_exp_f32_e32 v85, v85
	v_fma_f32 v38, v38, s72, -v159
	v_exp_f32_e32 v37, v37
	s_waitcnt lgkmcnt(5)
	v_mfma_f32_32x32x16_bf16 v[20:35], v[234:237], v[136:139], v[20:35]
	ds_read_b128 v[164:167], v155 offset:0
	ds_read_b128 v[168:171], v155 offset:6656
	v_fma_f32 v87, v87, s72, -v159
	v_add_f32_e32 v117, v84, v36
	v_exp_f32_e32 v86, v86
	v_fma_f32 v39, v39, s72, -v159
	v_exp_f32_e32 v38, v38
	v_cvt_pk_bf16_f32 v184, v84, v85
	v_fma_f32 v88, v88, s72, -v159
	s_waitcnt lgkmcnt(5)
	v_mfma_f32_32x32x16_bf16 v[4:19], v[238:241], v[132:135], v[4:19]
	ds_read_b128 v[250:253], v156 offset:51232
	ds_read_b128 v[172:175], v155 offset:32
	v_add_f32_e32 v118, v85, v37
	v_exp_f32_e32 v87, v87
	v_cvt_pk_bf16_f32 v192, v36, v37
	v_fma_f32 v40, v40, s72, -v159
	v_exp_f32_e32 v39, v39
	v_fma_f32 v89, v89, s72, -v159
	v_add_f32_e32 v119, v86, v38
	s_waitcnt lgkmcnt(5)
	v_mfma_f32_32x32x16_bf16 v[20:35], v[242:245], v[132:135], v[20:35]
	ds_read_b128 v[176:179], v155 offset:6688
	ds_read_b128 v[120:123], v156 offset:51264
	v_exp_f32_e32 v88, v88
	v_add_f32_e32 v116, v117, v118
	v_fma_f32 v41, v41, s72, -v159
	v_exp_f32_e32 v40, v40
	v_cvt_pk_bf16_f32 v185, v86, v87
	v_fma_f32 v90, v90, s72, -v159
	v_add_f32_e32 v220, v87, v39
	s_waitcnt lgkmcnt(5)
	v_mfma_f32_32x32x16_bf16 v[52:67], v[164:167], v[246:249], 0
	ds_read_b128 v[180:183], v155 offset:64
	ds_read_b128 v[124:127], v155 offset:6720
	v_exp_f32_e32 v89, v89
	v_add_f32_e32 v116, v116, v119
	v_cvt_pk_bf16_f32 v193, v38, v39
	v_fma_f32 v42, v42, s72, -v159
	v_exp_f32_e32 v41, v41
	v_fma_f32 v91, v91, s72, -v159
	v_add_f32_e32 v117, v88, v40
	s_waitcnt lgkmcnt(6)
	v_mfma_f32_32x32x16_bf16 v[68:83], v[168:171], v[246:249], 0
	ds_read_b128 v[246:249], v156 offset:51296
	v_exp_f32_e32 v90, v90
	v_add_f32_e32 v116, v116, v220
	v_fma_f32 v43, v43, s72, -v159
	v_exp_f32_e32 v42, v42
	v_cvt_pk_bf16_f32 v186, v88, v89
	v_fma_f32 v92, v92, s72, -v159
	v_add_f32_e32 v118, v89, v41
	s_waitcnt lgkmcnt(5)
	v_mfma_f32_32x32x16_bf16 v[52:67], v[172:175], v[250:253], v[52:67]
	ds_read_b128 v[128:131], v155 offset:96
	ds_read_b128 v[164:167], v155 offset:6752
	v_exp_f32_e32 v91, v91
	v_add_f32_e32 v116, v116, v117
	v_cvt_pk_bf16_f32 v194, v40, v41
	v_fma_f32 v44, v44, s72, -v159
	v_exp_f32_e32 v43, v43
	v_fma_f32 v93, v93, s72, -v159
	v_add_f32_e32 v119, v90, v42
	s_waitcnt lgkmcnt(6)
	v_mfma_f32_32x32x16_bf16 v[68:83], v[176:179], v[250:253], v[68:83]
	ds_read_b128 v[250:253], v156 offset:51328
	v_exp_f32_e32 v92, v92
	v_add_f32_e32 v116, v116, v118
	v_fma_f32 v45, v45, s72, -v159
	v_exp_f32_e32 v44, v44
	v_cvt_pk_bf16_f32 v187, v90, v91
	v_fma_f32 v94, v94, s72, -v159
	v_add_f32_e32 v220, v91, v43
	s_waitcnt lgkmcnt(5)
	v_mfma_f32_32x32x16_bf16 v[52:67], v[180:183], v[120:123], v[52:67]
	ds_read_b128 v[168:171], v155 offset:128
	ds_read_b128 v[172:175], v155 offset:6784
	v_exp_f32_e32 v93, v93
	v_add_f32_e32 v116, v116, v119
	v_cvt_pk_bf16_f32 v195, v42, v43
	v_fma_f32 v46, v46, s72, -v159
	v_exp_f32_e32 v45, v45
	v_fma_f32 v95, v95, s72, -v159
	v_add_f32_e32 v117, v92, v44
	s_waitcnt lgkmcnt(6)
	v_mfma_f32_32x32x16_bf16 v[68:83], v[124:127], v[120:123], v[68:83]
	ds_read_b128 v[120:123], v156 offset:51360
	v_exp_f32_e32 v94, v94
	v_add_f32_e32 v116, v116, v220
	v_fma_f32 v47, v47, s72, -v159
	v_exp_f32_e32 v46, v46
	v_cvt_pk_bf16_f32 v188, v92, v93
	v_fma_f32 v96, v96, s72, -v159
	v_add_f32_e32 v118, v93, v45
	s_waitcnt lgkmcnt(5)
	v_mfma_f32_32x32x16_bf16 v[52:67], v[128:131], v[246:249], v[52:67]
	ds_read_b128 v[176:179], v155 offset:160
	ds_read_b128 v[180:183], v155 offset:6816
	v_exp_f32_e32 v95, v95
	v_add_f32_e32 v116, v116, v117
	v_cvt_pk_bf16_f32 v196, v44, v45
	v_fma_f32 v48, v48, s72, -v159
	v_exp_f32_e32 v47, v47
	v_fma_f32 v97, v97, s72, -v159
	v_add_f32_e32 v119, v94, v46
	s_waitcnt lgkmcnt(6)
	v_mfma_f32_32x32x16_bf16 v[68:83], v[164:167], v[246:249], v[68:83]
	v_exp_f32_e32 v96, v96
	v_add_f32_e32 v116, v116, v118
	v_fma_f32 v49, v49, s72, -v159
	v_exp_f32_e32 v48, v48
	v_cvt_pk_bf16_f32 v189, v94, v95
	v_fma_f32 v98, v98, s72, -v159
	v_add_f32_e32 v220, v95, v47
	s_waitcnt lgkmcnt(4)
	v_mfma_f32_32x32x16_bf16 v[52:67], v[168:171], v[250:253], v[52:67]
	v_exp_f32_e32 v97, v97
	v_add_f32_e32 v116, v116, v119
	v_cvt_pk_bf16_f32 v197, v46, v47
	v_fma_f32 v50, v50, s72, -v159
	v_exp_f32_e32 v49, v49
	v_fma_f32 v99, v99, s72, -v159
	v_add_f32_e32 v117, v96, v48
	s_waitcnt lgkmcnt(3)
	v_mfma_f32_32x32x16_bf16 v[68:83], v[172:175], v[250:253], v[68:83]
	v_exp_f32_e32 v98, v98
	v_add_f32_e32 v116, v116, v220
	v_fma_f32 v51, v51, s72, -v159
	v_exp_f32_e32 v50, v50
	v_cvt_pk_bf16_f32 v190, v96, v97
	v_add_f32_e32 v118, v97, v49
	v_exp_f32_e32 v99, v99
	s_waitcnt lgkmcnt(1)
	v_mfma_f32_32x32x16_bf16 v[52:67], v[176:179], v[120:123], v[52:67]
	v_add_f32_e32 v116, v116, v117
	v_cvt_pk_bf16_f32 v198, v48, v49
	v_exp_f32_e32 v51, v51
	v_add_f32_e32 v119, v98, v50
	v_add_f32_e32 v116, v116, v118
	v_cvt_pk_bf16_f32 v191, v98, v99
	v_add_f32_e32 v220, v99, v51
	s_waitcnt lgkmcnt(0)
	v_mfma_f32_32x32x16_bf16 v[68:83], v[180:183], v[120:123], v[68:83]
	v_add_f32_e32 v116, v116, v119
	v_cvt_pk_bf16_f32 v199, v50, v51
	v_add_f32_e32 v116, v116, v220
	v_add_f32_e32 v152, v152, v116
	s_cmp_lg_u64 s[2:3], 0
	s_cbranch_scc1 .Lpa_nr0
	v_pk_mul_f32 v[4:5], v[112:113], v[4:5] op_sel_hi:[0,1]
	v_pk_mul_f32 v[6:7], v[112:113], v[6:7] op_sel_hi:[0,1]
	v_pk_mul_f32 v[8:9], v[112:113], v[8:9] op_sel_hi:[0,1]
	v_pk_mul_f32 v[10:11], v[112:113], v[10:11] op_sel_hi:[0,1]
	v_pk_mul_f32 v[12:13], v[112:113], v[12:13] op_sel_hi:[0,1]
	v_pk_mul_f32 v[14:15], v[112:113], v[14:15] op_sel_hi:[0,1]
	v_pk_mul_f32 v[16:17], v[112:113], v[16:17] op_sel_hi:[0,1]
	v_pk_mul_f32 v[18:19], v[112:113], v[18:19] op_sel_hi:[0,1]
	v_pk_mul_f32 v[20:21], v[112:113], v[20:21] op_sel_hi:[0,1]
	v_pk_mul_f32 v[22:23], v[112:113], v[22:23] op_sel_hi:[0,1]
	v_pk_mul_f32 v[24:25], v[112:113], v[24:25] op_sel_hi:[0,1]
	v_pk_mul_f32 v[26:27], v[112:113], v[26:27] op_sel_hi:[0,1]
	v_pk_mul_f32 v[28:29], v[112:113], v[28:29] op_sel_hi:[0,1]
	v_pk_mul_f32 v[30:31], v[112:113], v[30:31] op_sel_hi:[0,1]
	v_pk_mul_f32 v[32:33], v[112:113], v[32:33] op_sel_hi:[0,1]
	v_pk_mul_f32 v[34:35], v[112:113], v[34:35] op_sel_hi:[0,1]
.Lpa_nr0:
	s_waitcnt vmcnt(1)
	ds_write_b128 v157, v[104:107] offset:13312
	ds_write_b64 v158, v[108:109] offset:13440
	s_waitcnt vmcnt(0)
	ds_write_b128 v151, v[100:103] offset:38912
	s_waitcnt lgkmcnt(0)
	s_barrier
	buffer_load_dwordx2 v[108:109], v161, s[12:15], s52 offen
	s_add_i32 s3, s53, 0xfe040000
	buffer_load_dwordx4 v[104:107], v150, s[12:15], s3 offen
	buffer_load_dwordx4 v[100:103], v150, s[12:15], s53 offen
	ds_read_b64_tr_b16 v[200:201], v162 offset:38912
	ds_read_b64_tr_b16 v[202:203], v162 offset:40448
	ds_read_b64_tr_b16 v[204:205], v162 offset:38976
	ds_read_b64_tr_b16 v[206:207], v162 offset:40512
	ds_read_b64_tr_b16 v[208:209], v162 offset:41984
	ds_read_b64_tr_b16 v[210:211], v162 offset:43520
	ds_read_b64_tr_b16 v[212:213], v162 offset:42048
	ds_read_b64_tr_b16 v[214:215], v162 offset:43584
	v_max3_f32 v2, v52, v68, v53
	v_max3_f32 v110, v69, v54, v70
	v_max3_f32 v2, v2, v55, v71
	v_max3_f32 v110, v110, v56, v72
	s_waitcnt lgkmcnt(6)
	v_mfma_f32_32x32x16_bf16 v[4:19], v[200:203], v[184:187], v[4:19]
	ds_read_b64_tr_b16 v[216:217], v162 offset:45056
	v_max3_f32 v2, v2, v57, v73
	v_max3_f32 v110, v110, v58, v74
	v_max3_f32 v2, v2, v59, v75
	v_max3_f32 v110, v110, v60, v76
	v_max3_f32 v2, v2, v61, v77
	v_max3_f32 v110, v110, v62, v78
	v_max3_f32 v2, v2, v63, v79
	s_waitcnt lgkmcnt(5)
	v_mfma_f32_32x32x16_bf16 v[20:35], v[204:207], v[184:187], v[20:35]
	ds_read_b64_tr_b16 v[218:219], v162 offset:46592
	ds_read_b64_tr_b16 v[234:235], v162 offset:45120
	v_max3_f32 v110, v110, v64, v80
	v_max3_f32 v2, v2, v65, v81
	v_max3_f32 v110, v110, v66, v82
	v_max3_f32 v2, v2, v110, v67
	v_max_f32_e32 v2, v2, v83
	v_mov_b32_e32 v111, v2
	v_add_f32_e32 v115, 0x41000000, v159
	s_waitcnt lgkmcnt(5)
	v_mfma_f32_32x32x16_bf16 v[4:19], v[208:211], v[188:191], v[4:19]
	ds_read_b64_tr_b16 v[236:237], v162 offset:46656
	ds_read_b64_tr_b16 v[238:239], v162 offset:48128
	v_add_u32_e32 v163, 0, v162
	v_permlane32_swap_b32_e32 v2, v111
	v_max_f32_e32 v2, v2, v111
	v_mul_f32_e32 v2, 0x3e16c740, v2
	v_cmp_gt_f32_e32 vcc, v2, v115
	v_max_f32_e32 v114, v159, v2
	v_sub_f32_e32 v112, v159, v114
	s_waitcnt lgkmcnt(5)
	v_mfma_f32_32x32x16_bf16 v[20:35], v[212:215], v[188:191], v[20:35]
	ds_read_b64_tr_b16 v[240:241], v162 offset:49664
	ds_read_b64_tr_b16 v[242:243], v162 offset:48192
	v_exp_f32_e32 v112, v112
	s_cmp_eq_u64 vcc, 0
	s_cselect_b64 s[2:3], -1, 0
	v_cndmask_b32_e64 v159, v114, v159, s[2:3]
	v_mul_f32_e32 v116, v152, v112
	v_cndmask_b32_e64 v152, v116, v152, s[2:3]
	v_fma_f32 v52, v52, s72, -v159
	v_fma_f32 v68, v68, s72, -v159
	v_fma_f32 v53, v53, s72, -v159
	s_waitcnt lgkmcnt(5)
	v_mfma_f32_32x32x16_bf16 v[4:19], v[216:219], v[192:195], v[4:19]
	ds_read_b64_tr_b16 v[244:245], v162 offset:49728
	ds_read_b128 v[246:249], v156 offset:51200
	v_exp_f32_e32 v52, v52
	v_fma_f32 v69, v69, s72, -v159
	v_exp_f32_e32 v68, v68
	v_fma_f32 v54, v54, s72, -v159
	v_exp_f32_e32 v53, v53
	v_fma_f32 v70, v70, s72, -v159
	v_exp_f32_e32 v69, v69
	s_waitcnt lgkmcnt(5)
	v_mfma_f32_32x32x16_bf16 v[20:35], v[234:237], v[192:195], v[20:35]
	ds_read_b128 v[164:167], v155 offset:13312
	ds_read_b128 v[168:171], v155 offset:19968
	v_fma_f32 v55, v55, s72, -v159
	v_add_f32_e32 v117, v52, v68
	v_exp_f32_e32 v54, v54
	v_fma_f32 v71, v71, s72, -v159
	v_exp_f32_e32 v70, v70
	v_cvt_pk_bf16_f32 v144, v52, v53
	v_fma_f32 v56, v56, s72, -v159
	s_waitcnt lgkmcnt(5)
	v_mfma_f32_32x32x16_bf16 v[4:19], v[238:241], v[196:199], v[4:19]
	ds_read_b128 v[250:253], v156 offset:51232
	ds_read_b128 v[172:175], v155 offset:13344
	v_add_f32_e32 v118, v53, v69
	v_exp_f32_e32 v55, v55
	v_cvt_pk_bf16_f32 v136, v68, v69
	v_fma_f32 v72, v72, s72, -v159
	v_exp_f32_e32 v71, v71
	v_fma_f32 v57, v57, s72, -v159
	v_add_f32_e32 v119, v54, v70
	s_waitcnt lgkmcnt(5)
	v_mfma_f32_32x32x16_bf16 v[20:35], v[242:245], v[196:199], v[20:35]
	ds_read_b128 v[176:179], v155 offset:20000
	ds_read_b128 v[120:123], v156 offset:51264
	v_exp_f32_e32 v56, v56
	v_add_f32_e32 v116, v117, v118
	v_fma_f32 v73, v73, s72, -v159
	v_exp_f32_e32 v72, v72
	v_cvt_pk_bf16_f32 v145, v54, v55
	v_fma_f32 v58, v58, s72, -v159
	v_add_f32_e32 v220, v55, v71
	s_waitcnt lgkmcnt(5)
	v_mfma_f32_32x32x16_bf16 v[84:99], v[164:167], v[246:249], 0
	ds_read_b128 v[180:183], v155 offset:13376
	ds_read_b128 v[124:127], v155 offset:20032
	v_exp_f32_e32 v57, v57
	v_add_f32_e32 v116, v116, v119
	v_cvt_pk_bf16_f32 v137, v70, v71
	v_fma_f32 v74, v74, s72, -v159
	v_exp_f32_e32 v73, v73
	v_fma_f32 v59, v59, s72, -v159
	v_add_f32_e32 v117, v56, v72
	s_waitcnt lgkmcnt(6)
	v_mfma_f32_32x32x16_bf16 v[36:51], v[168:171], v[246:249], 0
	ds_read_b128 v[246:249], v156 offset:51296
	v_exp_f32_e32 v58, v58
	v_add_f32_e32 v116, v116, v220
	v_fma_f32 v75, v75, s72, -v159
	v_exp_f32_e32 v74, v74
	v_cvt_pk_bf16_f32 v146, v56, v57
	v_fma_f32 v60, v60, s72, -v159
	v_add_f32_e32 v118, v57, v73
	s_waitcnt lgkmcnt(5)
	v_mfma_f32_32x32x16_bf16 v[84:99], v[172:175], v[250:253], v[84:99]
	ds_read_b128 v[128:131], v155 offset:13408
	ds_read_b128 v[164:167], v155 offset:20064
	v_exp_f32_e32 v59, v59
	v_add_f32_e32 v116, v116, v117
	v_cvt_pk_bf16_f32 v138, v72, v73
	v_fma_f32 v76, v76, s72, -v159
	v_exp_f32_e32 v75, v75
	v_fma_f32 v61, v61, s72, -v159
	v_add_f32_e32 v119, v58, v74
	s_waitcnt lgkmcnt(6)
	v_mfma_f32_32x32x16_bf16 v[36:51], v[176:179], v[250:253], v[36:51]
	ds_read_b128 v[250:253], v156 offset:51328
	v_exp_f32_e32 v60, v60
	v_add_f32_e32 v116, v116, v118
	v_fma_f32 v77, v77, s72, -v159
	v_exp_f32_e32 v76, v76
	v_cvt_pk_bf16_f32 v147, v58, v59
	v_fma_f32 v62, v62, s72, -v159
	v_add_f32_e32 v220, v59, v75
	s_waitcnt lgkmcnt(5)
	v_mfma_f32_32x32x16_bf16 v[84:99], v[180:183], v[120:123], v[84:99]
	ds_read_b128 v[168:171], v155 offset:13440
	ds_read_b128 v[172:175], v155 offset:20096
	v_exp_f32_e32 v61, v61
	v_add_f32_e32 v116, v116, v119
	v_cvt_pk_bf16_f32 v139, v74, v75
	v_fma_f32 v78, v78, s72, -v159
	v_exp_f32_e32 v77, v77
	v_fma_f32 v63, v63, s72, -v159
	v_add_f32_e32 v117, v60, v76
	s_waitcnt lgkmcnt(6)
	v_mfma_f32_32x32x16_bf16 v[36:51], v[124:127], v[120:123], v[36:51]
	ds_read_b128 v[120:123], v156 offset:51360
	v_exp_f32_e32 v62, v62
	v_add_f32_e32 v116, v116, v220
	v_fma_f32 v79, v79, s72, -v159
	v_exp_f32_e32 v78, v78
	v_cvt_pk_bf16_f32 v140, v60, v61
	v_fma_f32 v64, v64, s72, -v159
	v_add_f32_e32 v118, v61, v77
	s_waitcnt lgkmcnt(5)
	v_mfma_f32_32x32x16_bf16 v[84:99], v[128:131], v[246:249], v[84:99]
	ds_read_b128 v[176:179], v155 offset:13472
	ds_read_b128 v[180:183], v155 offset:20128
	v_exp_f32_e32 v63, v63
	v_add_f32_e32 v116, v116, v117
	v_cvt_pk_bf16_f32 v132, v76, v77
	v_fma_f32 v80, v80, s72, -v159
	v_exp_f32_e32 v79, v79
	v_fma_f32 v65, v65, s72, -v159
	v_add_f32_e32 v119, v62, v78
	s_waitcnt lgkmcnt(6)
	v_mfma_f32_32x32x16_bf16 v[36:51], v[164:167], v[246:249], v[36:51]
	v_exp_f32_e32 v64, v64
	v_add_f32_e32 v116, v116, v118
	v_fma_f32 v81, v81, s72, -v159
	v_exp_f32_e32 v80, v80
	v_cvt_pk_bf16_f32 v141, v62, v63
	v_fma_f32 v66, v66, s72, -v159
	v_add_f32_e32 v220, v63, v79
	s_waitcnt lgkmcnt(4)
	v_mfma_f32_32x32x16_bf16 v[84:99], v[168:171], v[250:253], v[84:99]
	v_exp_f32_e32 v65, v65
	v_add_f32_e32 v116, v116, v119
	v_cvt_pk_bf16_f32 v133, v78, v79
	v_fma_f32 v82, v82, s72, -v159
	v_exp_f32_e32 v81, v81
	v_fma_f32 v67, v67, s72, -v159
	v_add_f32_e32 v117, v64, v80
	s_waitcnt lgkmcnt(3)
	v_mfma_f32_32x32x16_bf16 v[36:51], v[172:175], v[250:253], v[36:51]
	v_exp_f32_e32 v66, v66
	v_add_f32_e32 v116, v116, v220
	v_fma_f32 v83, v83, s72, -v159
	v_exp_f32_e32 v82, v82
	v_cvt_pk_bf16_f32 v142, v64, v65
	v_add_f32_e32 v118, v65, v81
	v_exp_f32_e32 v67, v67
	s_waitcnt lgkmcnt(1)
	v_mfma_f32_32x32x16_bf16 v[84:99], v[176:179], v[120:123], v[84:99]
	v_add_f32_e32 v116, v116, v117
	v_cvt_pk_bf16_f32 v134, v80, v81
	v_exp_f32_e32 v83, v83
	v_add_f32_e32 v119, v66, v82
	v_add_f32_e32 v116, v116, v118
	v_cvt_pk_bf16_f32 v143, v66, v67
	v_add_f32_e32 v220, v67, v83
	s_waitcnt lgkmcnt(0)
	v_mfma_f32_32x32x16_bf16 v[36:51], v[180:183], v[120:123], v[36:51]
	v_add_f32_e32 v116, v116, v119
	v_cvt_pk_bf16_f32 v135, v82, v83
	v_add_f32_e32 v116, v116, v220
	v_add_f32_e32 v152, v152, v116
	s_cmp_lg_u64 s[2:3], 0
	s_cbranch_scc1 .Lpa_nr1
	v_pk_mul_f32 v[4:5], v[112:113], v[4:5] op_sel_hi:[0,1]
	v_pk_mul_f32 v[6:7], v[112:113], v[6:7] op_sel_hi:[0,1]
	v_pk_mul_f32 v[8:9], v[112:113], v[8:9] op_sel_hi:[0,1]
	v_pk_mul_f32 v[10:11], v[112:113], v[10:11] op_sel_hi:[0,1]
	v_pk_mul_f32 v[12:13], v[112:113], v[12:13] op_sel_hi:[0,1]
	v_pk_mul_f32 v[14:15], v[112:113], v[14:15] op_sel_hi:[0,1]
	v_pk_mul_f32 v[16:17], v[112:113], v[16:17] op_sel_hi:[0,1]
	v_pk_mul_f32 v[18:19], v[112:113], v[18:19] op_sel_hi:[0,1]
	v_pk_mul_f32 v[20:21], v[112:113], v[20:21] op_sel_hi:[0,1]
	v_pk_mul_f32 v[22:23], v[112:113], v[22:23] op_sel_hi:[0,1]
	v_pk_mul_f32 v[24:25], v[112:113], v[24:25] op_sel_hi:[0,1]
	v_pk_mul_f32 v[26:27], v[112:113], v[26:27] op_sel_hi:[0,1]
	v_pk_mul_f32 v[28:29], v[112:113], v[28:29] op_sel_hi:[0,1]
	v_pk_mul_f32 v[30:31], v[112:113], v[30:31] op_sel_hi:[0,1]
	v_pk_mul_f32 v[32:33], v[112:113], v[32:33] op_sel_hi:[0,1]
	v_pk_mul_f32 v[34:35], v[112:113], v[34:35] op_sel_hi:[0,1]
.Lpa_nr1:
	s_waitcnt vmcnt(1)
	ds_write_b128 v157, v[104:107]
	ds_write_b64 v158, v[108:109] offset:128
	s_waitcnt vmcnt(0)
	ds_write_b128 v151, v[100:103] offset:26624
	s_add_i32 s51, s51, 2
	s_add_i32 s53, s53, 0x40000
	s_addk_i32 s52, 0x2000
	s_waitcnt lgkmcnt(0)
	s_barrier
	s_cmp_lt_i32 s51, s50
	s_cbranch_scc1 .LBB0_822
	s_branch .LBB0_860
